# baseline (speedup 1.0000x reference)
; #define LAS __attribute__((address_space(3)))
; __device__ __forceinline__ void unpack8(u32x4 w, float* f) { f[0] = bflo(w.x); f[1] = bfhi(w.x); f[2] = bflo(w.y); f[3] = bfhi(w.y); f[4] = bflo(w.z); f[5] = bfhi(w.z); f[6] = bflo(w.w); f[7] = bfhi(w.w); }
; __global__ void __launch_bounds__(512, 2) fwd_kernel(KP p) {
;     ...
;           for (int j = gw; j < 2 * DFF; j += NGW) { float a5[NSEQ] = {0.f, 0.f, 0.f, 0.f, 0.f};
; #pragma unroll
;               for (int i = 0; i < 4; ++i) { const int k = i * 512 + lane * 8; float wf[8]; unpack8(*(const u32x4*)(W13 + (size_t)j * DM + k), wf);
; #pragma unroll
;                   for (int sq = 0; sq < NSEQ; ++sq) { const f32x4 b0 = *(const LAS f32x4*)(b2s + sq * DM + k), b1 = *(const LAS f32x4*)(b2s + sq * DM + k + 4);
;                       a5[sq] += (wf[0] * b0.x + wf[1] * b0.y) + (wf[2] * b0.z + wf[3] * b0.w) + (wf[4] * b1.x + wf[5] * b1.y) + (wf[6] * b1.z + wf[7] * b1.w); } }
; #pragma unroll
;               for (int sq = 0; sq < NSEQ; ++sq) { const float t = wave_sum(a5[sq]); if (lane == 0) CB[(size_t)sq * (2 * DFF) + j] = t; } }
.LBB0_857:
	s_waitcnt lgkmcnt(0)
	v_lshl_add_u64 v[162:163], s[12:13], 0, v[160:161]
	v_add_co_u32_e32 v162, vcc, 0x4300000, v162
	s_add_u32 s18, s12, s0
	s_nop 0
	v_addc_co_u32_e32 v163, vcc, 0, v163, vcc
	global_load_dwordx4 v[182:185], v[162:163], off
	global_load_dwordx4 v[190:193], v[162:163], off offset:1024
	global_load_dwordx4 v[198:201], v[162:163], off offset:2048
	global_load_dwordx4 v[204:207], v[162:163], off offset:3072
	s_addc_u32 s19, s13, s1
	s_waitcnt vmcnt(3)
	v_lshlrev_b32_e32 v179, 16, v182
	v_and_b32_e32 v182, 0xffff0000, v182
	v_and_b32_e32 v181, 0xffff0000, v183
	v_lshlrev_b32_e32 v178, 16, v183
	v_lshlrev_b32_e32 v176, 16, v184
	v_and_b32_e32 v180, 0xffff0000, v184
	s_waitcnt lgkmcnt(14)
	v_mul_f32_e32 v183, v1, v182
	v_mul_f32_e32 v184, v3, v181
	v_fmac_f32_e32 v183, v0, v179
	v_fmac_f32_e32 v184, v2, v178
	v_add_f32_e32 v183, v183, v184
	v_mul_f32_e32 v184, v5, v180
	v_and_b32_e32 v177, 0xffff0000, v185
	v_fmac_f32_e32 v184, v4, v176
	v_lshlrev_b32_e32 v175, 16, v185
	v_add_f32_e32 v183, v183, v184
	v_mul_f32_e32 v184, v7, v177
	v_fmac_f32_e32 v184, v6, v175
	s_waitcnt vmcnt(2)
	v_lshlrev_b32_e32 v187, 16, v190
	v_and_b32_e32 v190, 0xffff0000, v190
	v_and_b32_e32 v189, 0xffff0000, v191
	v_add_f32_e32 v183, v184, v183
	v_lshlrev_b32_e32 v186, 16, v191
	v_lshlrev_b32_e32 v184, 16, v192
	v_and_b32_e32 v188, 0xffff0000, v192
	v_mul_f32_e32 v191, v41, v190
	v_mul_f32_e32 v192, v43, v189
	v_fmac_f32_e32 v191, v40, v187
	v_fmac_f32_e32 v192, v42, v186
	v_add_f32_e32 v191, v191, v192
	v_mul_f32_e32 v192, v45, v188
	v_and_b32_e32 v185, 0xffff0000, v193
	v_fmac_f32_e32 v192, v44, v184
	v_add_f32_e32 v194, 0, v183
	v_lshlrev_b32_e32 v183, 16, v193
	v_add_f32_e32 v191, v191, v192
	v_mul_f32_e32 v192, v47, v185
	v_fmac_f32_e32 v192, v46, v183
	v_add_f32_e32 v191, v192, v191
	s_waitcnt vmcnt(1)
	v_lshlrev_b32_e32 v195, 16, v198
	v_and_b32_e32 v198, 0xffff0000, v198
	v_and_b32_e32 v197, 0xffff0000, v199
	v_add_f32_e32 v202, v194, v191
	v_lshlrev_b32_e32 v194, 16, v199
	v_lshlrev_b32_e32 v192, 16, v200
	v_and_b32_e32 v196, 0xffff0000, v200
	v_mul_f32_e32 v199, v81, v198
	v_mul_f32_e32 v200, v83, v197
	v_fmac_f32_e32 v199, v80, v195
	v_fmac_f32_e32 v200, v82, v194
	v_add_f32_e32 v199, v199, v200
	v_mul_f32_e32 v200, v85, v196
	v_and_b32_e32 v193, 0xffff0000, v201
	v_fmac_f32_e32 v200, v84, v192
	v_lshlrev_b32_e32 v191, 16, v201
	v_add_f32_e32 v199, v199, v200
	v_mul_f32_e32 v200, v87, v193
	v_fmac_f32_e32 v200, v86, v191
	v_add_f32_e32 v199, v200, v199
	s_waitcnt vmcnt(0)
	v_lshlrev_b32_e32 v201, 16, v204
	v_and_b32_e32 v204, 0xffff0000, v204
	v_and_b32_e32 v203, 0xffff0000, v205
	v_add_f32_e32 v208, v202, v199
	v_lshlrev_b32_e32 v200, 16, v205
	v_lshlrev_b32_e32 v163, 16, v206
	v_and_b32_e32 v202, 0xffff0000, v206
	s_waitcnt lgkmcnt(9)
	v_mul_f32_e32 v205, v121, v204
	v_mul_f32_e32 v206, v123, v203
	v_fmac_f32_e32 v205, v120, v201
	v_fmac_f32_e32 v206, v122, v200
	v_add_f32_e32 v205, v205, v206
	s_waitcnt lgkmcnt(8)
	v_mul_f32_e32 v206, v125, v202
	v_and_b32_e32 v199, 0xffff0000, v207
	v_fmac_f32_e32 v206, v124, v163
	v_lshlrev_b32_e32 v162, 16, v207
	v_add_f32_e32 v205, v205, v206
	v_mul_f32_e32 v206, v127, v199
	v_fmac_f32_e32 v206, v126, v162
	v_add_f32_e32 v205, v206, v205
	v_add_f32_e32 v205, v208, v205
	v_mov_b32_e32 v209, v205
	v_mul_f32_e32 v205, v9, v182
	s_waitcnt lgkmcnt(0)
	v_mul_f32_e32 v206, v11, v181
	v_fmac_f32_e32 v205, v8, v179
	v_fmac_f32_e32 v206, v10, v178
	v_add_f32_e32 v205, v205, v206
	v_mul_f32_e32 v206, v13, v180
	v_fmac_f32_e32 v206, v12, v176
	v_add_f32_e32 v205, v205, v206
	v_mul_f32_e32 v206, v15, v177
	v_fmac_f32_e32 v206, v14, v175
	v_add_f32_e32 v205, v206, v205
	v_mul_f32_e32 v206, v49, v190
	v_mul_f32_e32 v207, v51, v189
	v_fmac_f32_e32 v206, v48, v187
	v_fmac_f32_e32 v207, v50, v186
	v_add_f32_e32 v206, v206, v207
	v_mul_f32_e32 v207, v53, v188
	v_fmac_f32_e32 v207, v52, v184
	v_add_f32_e32 v206, v206, v207
	v_mul_f32_e32 v207, v55, v185
	v_fmac_f32_e32 v207, v54, v183
	v_add_f32_e32 v205, 0, v205
	v_add_f32_e32 v206, v207, v206
	v_add_f32_e32 v205, v205, v206
	v_mul_f32_e32 v206, v89, v198
	v_mul_f32_e32 v207, v91, v197
	v_fmac_f32_e32 v206, v88, v195
	v_fmac_f32_e32 v207, v90, v194
	v_add_f32_e32 v206, v206, v207
	v_mul_f32_e32 v207, v93, v196
	v_fmac_f32_e32 v207, v92, v192
	v_add_f32_e32 v206, v206, v207
	v_mul_f32_e32 v207, v95, v193
	v_fmac_f32_e32 v207, v94, v191
	v_add_f32_e32 v206, v207, v206
	v_add_f32_e32 v205, v205, v206
	v_mul_f32_e32 v206, v129, v204
	v_mul_f32_e32 v207, v131, v203
	v_fmac_f32_e32 v206, v128, v201
	v_fmac_f32_e32 v207, v130, v200
	v_add_f32_e32 v206, v206, v207
	v_mul_f32_e32 v207, v133, v202
	v_fmac_f32_e32 v207, v132, v163
	v_add_f32_e32 v206, v206, v207
	v_mul_f32_e32 v207, v135, v199
	v_fmac_f32_e32 v207, v134, v162
	v_add_f32_e32 v206, v207, v206
	v_add_f32_e32 v205, v205, v206
	v_mov_b32_e32 v210, v205
	v_mul_f32_e32 v205, v17, v182
	s_waitcnt lgkmcnt(0)
; #define LAS __attribute__((address_space(3)))
; __device__ __forceinline__ void unpack8(u32x4 w, float* f) { f[0] = bflo(w.x); f[1] = bfhi(w.x); f[2] = bflo(w.y); f[3] = bfhi(w.y); f[4] = bflo(w.z); f[5] = bfhi(w.z); f[6] = bflo(w.w); f[7] = bfhi(w.w); }
; __global__ void __launch_bounds__(512, 2) fwd_kernel(KP p) {
;     ...
;           for (int j = gw; j < 2 * DFF; j += NGW) { float a5[NSEQ] = {0.f, 0.f, 0.f, 0.f, 0.f};
; #pragma unroll
;               for (int i = 0; i < 4; ++i) { const int k = i * 512 + lane * 8; float wf[8]; unpack8(*(const u32x4*)(W13 + (size_t)j * DM + k), wf);
; #pragma unroll
;                   for (int sq = 0; sq < NSEQ; ++sq) { const f32x4 b0 = *(const LAS f32x4*)(b2s + sq * DM + k), b1 = *(const LAS f32x4*)(b2s + sq * DM + k + 4);
;                       a5[sq] += (wf[0] * b0.x + wf[1] * b0.y) + (wf[2] * b0.z + wf[3] * b0.w) + (wf[4] * b1.x + wf[5] * b1.y) + (wf[6] * b1.z + wf[7] * b1.w); } }
; #pragma unroll
;               for (int sq = 0; sq < NSEQ; ++sq) { const float t = wave_sum(a5[sq]); if (lane == 0) CB[(size_t)sq * (2 * DFF) + j] = t; } }
	v_mul_f32_e32 v206, v19, v181
	v_fmac_f32_e32 v205, v16, v179
	v_fmac_f32_e32 v206, v18, v178
	v_add_f32_e32 v205, v205, v206
	v_mul_f32_e32 v206, v21, v180
	v_fmac_f32_e32 v206, v20, v176
	v_add_f32_e32 v205, v205, v206
	v_mul_f32_e32 v206, v23, v177
	v_fmac_f32_e32 v206, v22, v175
	v_add_f32_e32 v205, v206, v205
	v_mul_f32_e32 v206, v57, v190
	v_mul_f32_e32 v207, v59, v189
	v_fmac_f32_e32 v206, v56, v187
	v_fmac_f32_e32 v207, v58, v186
	v_add_f32_e32 v206, v206, v207
	v_mul_f32_e32 v207, v61, v188
	v_fmac_f32_e32 v207, v60, v184
	v_add_f32_e32 v206, v206, v207
	v_mul_f32_e32 v207, v63, v185
	v_fmac_f32_e32 v207, v62, v183
	v_add_f32_e32 v205, 0, v205
	v_add_f32_e32 v206, v207, v206
	v_add_f32_e32 v205, v205, v206
	v_mul_f32_e32 v206, v97, v198
	v_mul_f32_e32 v207, v99, v197
	v_fmac_f32_e32 v206, v96, v195
	v_fmac_f32_e32 v207, v98, v194
	v_add_f32_e32 v206, v206, v207
	v_mul_f32_e32 v207, v101, v196
	v_fmac_f32_e32 v207, v100, v192
	v_add_f32_e32 v206, v206, v207
	v_mul_f32_e32 v207, v103, v193
	v_fmac_f32_e32 v207, v102, v191
	v_add_f32_e32 v206, v207, v206
	v_add_f32_e32 v205, v205, v206
	v_mul_f32_e32 v206, v137, v204
	v_mul_f32_e32 v207, v139, v203
	v_fmac_f32_e32 v206, v136, v201
	v_fmac_f32_e32 v207, v138, v200
	v_add_f32_e32 v206, v206, v207
	v_mul_f32_e32 v207, v141, v202
	v_fmac_f32_e32 v207, v140, v163
	v_add_f32_e32 v206, v206, v207
	v_mul_f32_e32 v207, v143, v199
	v_fmac_f32_e32 v207, v142, v162
	v_add_f32_e32 v206, v207, v206
	v_add_f32_e32 v205, v205, v206
	v_mov_b32_e32 v211, v205
	v_mul_f32_e32 v205, v25, v182
	s_waitcnt lgkmcnt(0)
	v_mul_f32_e32 v206, v27, v181
	v_fmac_f32_e32 v205, v24, v179
	v_fmac_f32_e32 v206, v26, v178
	v_add_f32_e32 v205, v205, v206
	v_mul_f32_e32 v206, v29, v180
	v_fmac_f32_e32 v206, v28, v176
	v_add_f32_e32 v205, v205, v206
	v_mul_f32_e32 v206, v31, v177
	v_fmac_f32_e32 v206, v30, v175
	v_add_f32_e32 v205, v206, v205
	v_mul_f32_e32 v206, v65, v190
	v_mul_f32_e32 v207, v67, v189
	v_fmac_f32_e32 v206, v64, v187
	v_fmac_f32_e32 v207, v66, v186
	v_add_f32_e32 v206, v206, v207
	v_mul_f32_e32 v207, v69, v188
	v_fmac_f32_e32 v207, v68, v184
	v_add_f32_e32 v206, v206, v207
	v_mul_f32_e32 v207, v71, v185
	v_fmac_f32_e32 v207, v70, v183
	v_add_f32_e32 v205, 0, v205
	v_add_f32_e32 v206, v207, v206
	v_add_f32_e32 v205, v205, v206
	v_mul_f32_e32 v206, v105, v198
	v_mul_f32_e32 v207, v107, v197
	v_fmac_f32_e32 v206, v104, v195
	v_fmac_f32_e32 v207, v106, v194
	v_add_f32_e32 v206, v206, v207
	v_mul_f32_e32 v207, v109, v196
	v_fmac_f32_e32 v207, v108, v192
	v_add_f32_e32 v206, v206, v207
	v_mul_f32_e32 v207, v111, v193
	v_fmac_f32_e32 v207, v110, v191
	v_add_f32_e32 v206, v207, v206
	v_add_f32_e32 v205, v205, v206
	v_mul_f32_e32 v206, v145, v204
	v_mul_f32_e32 v207, v147, v203
	v_fmac_f32_e32 v206, v144, v201
	v_fmac_f32_e32 v207, v146, v200
	v_add_f32_e32 v206, v206, v207
	v_mul_f32_e32 v207, v149, v202
	v_fmac_f32_e32 v207, v148, v163
	v_add_f32_e32 v206, v206, v207
	v_mul_f32_e32 v207, v151, v199
	v_fmac_f32_e32 v207, v150, v162
	v_add_f32_e32 v206, v207, v206
	v_add_f32_e32 v205, v205, v206
	v_mov_b32_e32 v212, v205
	v_mul_f32_e32 v182, v33, v182
	v_fmac_f32_e32 v182, v32, v179
	v_mul_f32_e32 v179, v35, v181
	v_fmac_f32_e32 v179, v34, v178
	v_add_f32_e32 v178, v182, v179
	v_mul_f32_e32 v179, v37, v180
	v_fmac_f32_e32 v179, v36, v176
	v_mul_f32_e32 v177, v39, v177
	v_add_f32_e32 v176, v178, v179
	v_fmac_f32_e32 v177, v38, v175
	v_add_f32_e32 v175, v177, v176
	v_mul_f32_e32 v176, v73, v190
	v_mul_f32_e32 v177, v75, v189
	v_fmac_f32_e32 v176, v72, v187
	v_fmac_f32_e32 v177, v74, v186
	v_add_f32_e32 v176, v176, v177
	v_mul_f32_e32 v177, v77, v188
	v_fmac_f32_e32 v177, v76, v184
	v_add_f32_e32 v176, v176, v177
	v_mul_f32_e32 v177, v79, v185
	v_fmac_f32_e32 v177, v78, v183
	v_add_f32_e32 v175, 0, v175
	v_add_f32_e32 v176, v177, v176
	v_add_f32_e32 v175, v175, v176
	v_mul_f32_e32 v176, v113, v198
	v_mul_f32_e32 v177, v115, v197
	v_fmac_f32_e32 v176, v112, v195
	v_fmac_f32_e32 v177, v114, v194
	v_add_f32_e32 v176, v176, v177
	v_mul_f32_e32 v177, v117, v196
	v_fmac_f32_e32 v177, v116, v192
	v_add_f32_e32 v176, v176, v177
	v_mul_f32_e32 v177, v119, v193
	v_fmac_f32_e32 v177, v118, v191
	v_add_f32_e32 v176, v177, v176
	v_add_f32_e32 v175, v175, v176
	v_mul_f32_e32 v176, v153, v204
	v_mul_f32_e32 v177, v155, v203
	v_fmac_f32_e32 v176, v152, v201
	v_fmac_f32_e32 v177, v154, v200
	v_add_f32_e32 v176, v176, v177
	v_mul_f32_e32 v177, v157, v202
	v_fmac_f32_e32 v177, v156, v163
	v_add_f32_e32 v163, v176, v177
	v_mul_f32_e32 v176, v159, v199
	v_fmac_f32_e32 v176, v158, v162
	v_add_f32_e32 v162, v176, v163
	v_add_f32_e32 v162, v175, v162
	ds_bpermute_b32 v213, v164, v209
	ds_bpermute_b32 v214, v164, v210
	ds_bpermute_b32 v215, v164, v211
	ds_bpermute_b32 v216, v164, v212
	ds_bpermute_b32 v217, v164, v162
	s_waitcnt lgkmcnt(0)
	v_add_f32_e32 v209, v209, v213
	v_add_f32_e32 v210, v210, v214
	v_add_f32_e32 v211, v211, v215
	v_add_f32_e32 v212, v212, v216
	v_add_f32_e32 v162, v162, v217
	ds_bpermute_b32 v213, v165, v209
	ds_bpermute_b32 v214, v165, v210
	ds_bpermute_b32 v215, v165, v211
	ds_bpermute_b32 v216, v165, v212
	ds_bpermute_b32 v217, v165, v162
	s_waitcnt lgkmcnt(0)
	v_add_f32_e32 v209, v209, v213
	v_add_f32_e32 v210, v210, v214
	v_add_f32_e32 v211, v211, v215
	v_add_f32_e32 v212, v212, v216
	v_add_f32_e32 v162, v162, v217
	ds_bpermute_b32 v213, v166, v209
	ds_bpermute_b32 v214, v166, v210
	ds_bpermute_b32 v215, v166, v211
	ds_bpermute_b32 v216, v166, v212
	ds_bpermute_b32 v217, v166, v162
	s_waitcnt lgkmcnt(0)
	v_add_f32_e32 v209, v209, v213
	v_add_f32_e32 v210, v210, v214
	v_add_f32_e32 v211, v211, v215
	v_add_f32_e32 v212, v212, v216
	v_add_f32_e32 v162, v162, v217
	ds_bpermute_b32 v213, v167, v209
	ds_bpermute_b32 v214, v167, v210
	ds_bpermute_b32 v215, v167, v211
	ds_bpermute_b32 v216, v167, v212
	ds_bpermute_b32 v217, v167, v162
	s_waitcnt lgkmcnt(0)
	v_add_f32_e32 v209, v209, v213
	v_add_f32_e32 v210, v210, v214
	v_add_f32_e32 v211, v211, v215
	v_add_f32_e32 v212, v212, v216
	v_add_f32_e32 v162, v162, v217
	ds_bpermute_b32 v213, v168, v209
	ds_bpermute_b32 v214, v168, v210
	ds_bpermute_b32 v215, v168, v211
	ds_bpermute_b32 v216, v168, v212
	ds_bpermute_b32 v217, v168, v162
	s_waitcnt lgkmcnt(0)
	v_add_f32_e32 v209, v209, v213
	v_add_f32_e32 v210, v210, v214
	v_add_f32_e32 v211, v211, v215
	v_add_f32_e32 v212, v212, v216
	v_add_f32_e32 v162, v162, v217
	ds_bpermute_b32 v213, v169, v209
	ds_bpermute_b32 v214, v169, v210
	ds_bpermute_b32 v215, v169, v211
	ds_bpermute_b32 v216, v169, v212
	ds_bpermute_b32 v217, v169, v162
	s_waitcnt lgkmcnt(0)
	v_add_f32_e32 v209, v209, v213
	v_add_f32_e32 v210, v210, v214
	v_add_f32_e32 v211, v211, v215
	v_add_f32_e32 v212, v212, v216
	v_add_f32_e32 v162, v162, v217
	s_and_saveexec_b64 s[24:25], s[36:37]
	s_cbranch_execz .LBB0_856
	global_store_dword v170, v209, s[18:19]
	global_store_dword v171, v210, s[18:19]
	global_store_dword v172, v211, s[18:19]
	global_store_dword v173, v212, s[18:19]
	global_store_dword v174, v162, s[18:19]
	s_branch .LBB0_856
